# layer-1 in-projection q/k epilogue: per-row xor16/xor32 LDS shuffles replaced by permlane16/32 swaps
# baseline (speedup 1.0000x reference)
; __device__ __forceinline__ unsigned cvt_pk_bf16(float lo, float hi) { f32x2_t v = {lo, hi}; bf16x2_t b = __builtin_convertvector(v, bf16x2_t); return __builtin_bit_cast(unsigned, b); }
;     __device__ __forceinline__ float rstd_of(int token, int part  ) const { const f32x4 p = *(const f32x4*)(ssq + (size_t)token * 16 + 4 * part); return (p[0] + p[1]) + (p[2] + p[3]); }
;     __device__ __forceinline__ void operator()(const f32x4 (&acc)[2][2][4][2], const Unit& u, int wr, int wc, int fr, int fq) const {
;         const int row0 = u.pm * BM + wr * 64 + fr;
;         if (u.sel == 1) {
;             const int col0 = u.pn * BM + wc * 32 + 8 * fq, bt = (u.pn * BM) / SEQ;
;             float mine; { const int k = fr, tok = col0 + (k >> 3) * HALF + ((k >> 2) & 1) * 4 + (k & 3);
;                 const float t = (rstd_of(tok, 0) + rstd_of(tok, 1)) + (rstd_of(tok, 2) + rstd_of(tok, 3)); mine = __builtin_amdgcn_rsqf(t * (1.0f / D) + EPS); }
;             f32x4 rs[2][2];
; #pragma unroll
;             for (int k = 0; k < 16; ++k) rs[k >> 3][(k >> 2) & 1][k & 3] = __shfl(mine, (fq << 4) | k);
; #pragma unroll
;             for (int ai = 0; ai < 2; ++ai)
; #pragma unroll
;                 for (int m = 0; m < 4; ++m) { const int hd = row0 + ai * HALF + m * 16; const float swv = sw[bt * 4096 + 2048 + hd]; bf16_t* rowp = VT + (size_t)hd * M + col0;
; #pragma unroll
;                     for (int bj = 0; bj < 2; ++bj) { const f32x4 v0 = acc[ai][bj][m][0] * rs[bj][0] + swv, v1 = acc[ai][bj][m][1] * rs[bj][1] + swv;
;                         u32x4 w; w.x = cvt_pk_bf16(v0[0], v0[1]); w.y = cvt_pk_bf16(v0[2], v0[3]); w.z = cvt_pk_bf16(v1[0], v1[1]); w.w = cvt_pk_bf16(v1[2], v1[3]);
;                         *(u32x4*)(rowp + bj * HALF) = w; } }
;             return;
;         }
;         const int bt = (u.pm * BM) / SEQ;
;         float rs[2][4];
; #pragma unroll
;         for (int ai = 0; ai < 2; ++ai)
; #pragma unroll
;             for (int m = 0; m < 4; ++m) { float t = rstd_of(row0 + ai * HALF + m * 16, fq); t += __shfl_xor(t, 16); t += __shfl_xor(t, 32); rs[ai][m] = __builtin_amdgcn_rsqf(t * (1.0f / D) + EPS); }
;         if (u.pn >= 8) {
.LBB0_474:
	v_lshl_add_u32 v192, s34, 8, v1
	v_or_b32_e32 v190, 16, v192
	v_or_b32_e32 v188, 32, v192
	v_or_b32_e32 v186, 48, v192
	v_add_u32_e32 v184, 0x80, v192
	v_add_u32_e32 v182, 0x90, v192
	v_add_u32_e32 v180, 0xa0, v192
	v_add_u32_e32 v178, 0xb0, v192
	s_mov_b64 s[36:37], -1
	s_cmp_lg_u32 s80, 1
	v_ashrrev_i32_e32 v193, 31, v192
	v_ashrrev_i32_e32 v191, 31, v190
	v_ashrrev_i32_e32 v189, 31, v188
	v_ashrrev_i32_e32 v187, 31, v186
	v_ashrrev_i32_e32 v185, 31, v184
	v_ashrrev_i32_e32 v183, 31, v182
	v_ashrrev_i32_e32 v181, 31, v180
	v_ashrrev_i32_e32 v179, 31, v178
	s_cbranch_scc0 .LBB0_481
	v_lshlrev_b64 v[130:131], 6, v[192:193]
	v_lshlrev_b64 v[132:133], 6, v[190:191]
	v_lshl_add_u64 v[130:131], v[172:173], 0, v[130:131]
	v_lshl_add_u64 v[134:135], v[172:173], 0, v[132:133]
	v_lshlrev_b64 v[138:139], 6, v[188:189]
	v_lshlrev_b64 v[140:141], 6, v[186:187]
	v_lshlrev_b64 v[146:147], 6, v[184:185]
	v_lshlrev_b64 v[148:149], 6, v[182:183]
	global_load_dwordx4 v[130:133], v[130:131], off
	s_nop 0
	global_load_dwordx4 v[134:137], v[134:135], off
	v_lshl_add_u64 v[138:139], v[172:173], 0, v[138:139]
	v_lshl_add_u64 v[142:143], v[172:173], 0, v[140:141]
	v_lshl_add_u64 v[146:147], v[172:173], 0, v[146:147]
	v_lshl_add_u64 v[150:151], v[172:173], 0, v[148:149]
	global_load_dwordx4 v[138:141], v[138:139], off
	s_nop 0
	global_load_dwordx4 v[142:145], v[142:143], off
	s_nop 0
	global_load_dwordx4 v[146:149], v[146:147], off
	s_nop 0
	global_load_dwordx4 v[150:153], v[150:151], off
	v_lshlrev_b64 v[154:155], 6, v[180:181]
	v_lshlrev_b64 v[158:159], 6, v[178:179]
	v_lshl_add_u64 v[154:155], v[172:173], 0, v[154:155]
	v_lshl_add_u64 v[158:159], v[172:173], 0, v[158:159]
	global_load_dwordx4 v[154:157], v[154:155], off
	v_and_b32_e32 v194, 64, v241
	global_load_dwordx4 v[158:161], v[158:159], off
	v_xor_b32_e32 v170, 16, v241
	v_add_u32_e32 v194, 64, v194
	v_cmp_lt_i32_e32 vcc, v170, v194
	v_xor_b32_e32 v196, 32, v241
	s_ashr_i32 s23, s34, 31
	v_cndmask_b32_e32 v170, v241, v170, vcc
	v_lshlrev_b32_e32 v244, 2, v170
	v_cmp_lt_i32_e32 vcc, v196, v194
	s_lshr_b32 s23, s23, 27
	s_add_i32 s23, s34, s23
	v_cndmask_b32_e32 v194, v241, v196, vcc
	v_lshlrev_b32_e32 v243, 2, v194
	s_ashr_i32 s23, s23, 5
	s_mov_b64 s[34:35], -1
	s_cmp_lt_i32 s30, 8
	v_lshlrev_b64 v[218:219], 11, v[192:193]
	v_lshlrev_b64 v[214:215], 11, v[190:191]
	v_lshlrev_b64 v[210:211], 11, v[188:189]
	v_lshlrev_b64 v[206:207], 11, v[186:187]
	v_lshlrev_b64 v[202:203], 11, v[184:185]
	s_waitcnt vmcnt(0)
	v_add_f32_e32 v130, v130, v131
	v_add_f32_e32 v131, v132, v133
	v_add_f32_e32 v132, v134, v135
	v_add_f32_e32 v133, v136, v137
	v_add_f32_e32 v130, v130, v131
	v_add_f32_e32 v134, v138, v139
	v_add_f32_e32 v135, v140, v141
	v_add_f32_e32 v138, v146, v147
	v_add_f32_e32 v139, v148, v149
	v_add_f32_e32 v131, v132, v133
	v_add_f32_e32 v132, v134, v135
	v_add_f32_e32 v134, v138, v139
	ds_bpermute_b32 v138, v244, v130
	v_add_f32_e32 v136, v142, v143
	v_add_f32_e32 v137, v144, v145
	v_add_f32_e32 v140, v150, v151
	v_add_f32_e32 v141, v152, v153
	v_add_f32_e32 v142, v154, v155
	v_add_f32_e32 v143, v156, v157
	v_add_f32_e32 v144, v158, v159
	v_add_f32_e32 v145, v160, v161
	ds_bpermute_b32 v139, v244, v131
	s_waitcnt lgkmcnt(1)
	v_add_f32_e32 v130, v130, v138
	v_add_f32_e32 v133, v136, v137
	v_add_f32_e32 v135, v140, v141
	v_add_f32_e32 v136, v142, v143
	v_add_f32_e32 v137, v144, v145
	ds_bpermute_b32 v138, v243, v130
	ds_bpermute_b32 v140, v244, v132
	ds_bpermute_b32 v141, v244, v133
	ds_bpermute_b32 v142, v244, v134
	ds_bpermute_b32 v143, v244, v135
	ds_bpermute_b32 v144, v244, v136
	ds_bpermute_b32 v145, v244, v137
	s_waitcnt lgkmcnt(7)
	v_add_f32_e32 v131, v131, v139
	ds_bpermute_b32 v139, v243, v131
	s_waitcnt lgkmcnt(7)
	v_add_f32_e32 v130, v130, v138
	s_waitcnt lgkmcnt(6)
	v_add_f32_e32 v132, v132, v140
	s_waitcnt lgkmcnt(5)
	v_add_f32_e32 v133, v133, v141
	s_waitcnt lgkmcnt(4)
	v_add_f32_e32 v134, v134, v142
	s_waitcnt lgkmcnt(3)
	v_add_f32_e32 v135, v135, v143
	s_waitcnt lgkmcnt(2)
	v_add_f32_e32 v136, v136, v144
	s_waitcnt lgkmcnt(1)
	v_add_f32_e32 v137, v137, v145
	v_fmamk_f32 v130, v130, 0x3a800000, v239
	ds_bpermute_b32 v140, v243, v132
	ds_bpermute_b32 v141, v243, v133
	ds_bpermute_b32 v142, v243, v134
	ds_bpermute_b32 v143, v243, v135
	ds_bpermute_b32 v144, v243, v136
	v_rsq_f32_e32 v216, v130
	ds_bpermute_b32 v130, v243, v137
	s_waitcnt lgkmcnt(6)
	v_add_f32_e32 v131, v131, v139
	v_fmamk_f32 v131, v131, 0x3a800000, v239
	s_waitcnt lgkmcnt(5)
	v_add_f32_e32 v132, v132, v140
	s_waitcnt lgkmcnt(4)
	v_add_f32_e32 v133, v133, v141
	s_waitcnt lgkmcnt(3)
	v_add_f32_e32 v134, v134, v142
	s_waitcnt lgkmcnt(2)
	v_add_f32_e32 v135, v135, v143
	v_rsq_f32_e32 v212, v131
	s_waitcnt lgkmcnt(1)
	v_add_f32_e32 v131, v136, v144
	s_waitcnt lgkmcnt(0)
	v_add_f32_e32 v130, v137, v130
	v_fmamk_f32 v132, v132, 0x3a800000, v239
	v_fmamk_f32 v133, v133, 0x3a800000, v239
	v_fmamk_f32 v134, v134, 0x3a800000, v239
	v_fmamk_f32 v135, v135, 0x3a800000, v239
	v_fmamk_f32 v131, v131, 0x3a800000, v239
	v_fmamk_f32 v130, v130, 0x3a800000, v239
	v_rsq_f32_e32 v208, v132
	v_rsq_f32_e32 v204, v133
	v_rsq_f32_e32 v200, v134
	v_rsq_f32_e32 v198, v135
	v_rsq_f32_e32 v196, v131
	v_rsq_f32_e32 v194, v130
	s_cbranch_scc0 .LBB0_477
; __device__ __forceinline__ unsigned cvt_pk_bf16(float lo, float hi) { f32x2_t v = {lo, hi}; bf16x2_t b = __builtin_convertvector(v, bf16x2_t); return __builtin_bit_cast(unsigned, b); }
;     __device__ __forceinline__ void operator()(const f32x4 (&acc)[2][2][4][2], const Unit& u, int wr, int wc, int fr, int fq) const {
;     ...
;             const bool isq = u.pn < 4; bf16_t* O = Q + (size_t)(u.pn >> 2) * ((size_t)M * D); const float* nw = qn; if (!isq) nw = kn; const float sc = isq ? (LOG2E * 0.125f) : 1.0f;
;             const int col0 = (u.pn & 3) * BM + 64 * wc + 8 * fq;
;             f32x4 w4[2][2], s4[2][2];
; #pragma unroll
;             for (int bj = 0; bj < 2; ++bj)
; #pragma unroll
;                 for (int n = 0; n < 2; ++n) { w4[bj][n] = *(const f32x4*)(nw + 32 * bj + 8 * fq + 4 * n); s4[bj][n] = *(const f32x4*)(sw + bt * 4096 + (u.pn >> 2) * 1024 + col0 + 32 * bj + 4 * n); }
; #pragma unroll
;             for (int ai = 0; ai < 2; ++ai)
; #pragma unroll
;                 for (int m = 0; m < 4; ++m) {
;                     f32x4 v[2][2]; float ss = 0.f;
; #pragma unroll
;                     for (int bj = 0; bj < 2; ++bj)
; #pragma unroll
;                         for (int n = 0; n < 2; ++n) { v[bj][n] = acc[ai][bj][m][n] * rs[ai][m] + s4[bj][n]; const f32x4 t = v[bj][n]; ss += (t[0] * t[0] + t[1] * t[1]) + (t[2] * t[2] + t[3] * t[3]); }
;                     ss += __shfl_xor(ss, 16); ss += __shfl_xor(ss, 32);
;                     const float rq = __builtin_amdgcn_rsqf(ss * (1.0f / 64.0f) + EPS) * sc;
;                     bf16_t* rowp = O + (size_t)(row0 + ai * HALF + m * 16) * D + col0;
; #pragma unroll
;                     for (int bj = 0; bj < 2; ++bj) { const f32x4 v0 = v[bj][0] * rq * w4[bj][0], v1 = v[bj][1] * rq * w4[bj][1];
;                         u32x4 w; w.x = cvt_pk_bf16(v0[0], v0[1]); w.y = cvt_pk_bf16(v0[2], v0[3]); w.z = cvt_pk_bf16(v1[0], v1[1]); w.w = cvt_pk_bf16(v1[2], v1[3]);
;                         *(u32x4*)(rowp + 32 * bj) = w; } }
	s_ashr_i32 s34, s30, 2
	s_ashr_i32 s35, s34, 31
	s_lshl_b64 s[34:35], s[34:35], 25
	s_add_u32 s34, s64, s34
	s_addc_u32 s35, s65, s35
	s_cmp_lt_i32 s30, 4
	s_cselect_b64 vcc, -1, 0
	s_and_b64 s[36:37], vcc, exec
	s_cselect_b32 s37, s45, s47
	s_cselect_b32 s36, s44, s46
	s_lshl_b32 s25, s30, 8
	s_and_b32 s38, s25, 0x300
	v_or_b32_e32 v170, s38, v209
	s_lshl_b32 s38, s23, 12
	s_ashr_i32 s39, s38, 31
	s_lshl_b64 s[38:39], s[38:39], 2
	s_add_u32 s40, s14, s38
	s_addc_u32 s41, s15, s39
	s_and_b32 s38, s25, 0xfffffc00
	s_ashr_i32 s39, s38, 31
	s_lshl_b64 s[38:39], s[38:39], 2
	s_add_u32 s38, s40, s38
	v_lshlrev_b32_e32 v150, 2, v170
	s_addc_u32 s39, s41, s39
	global_load_dwordx4 v[138:141], v240, s[36:37] offset:16
	global_load_dwordx4 v[142:145], v240, s[36:37]
	global_load_dwordx4 v[154:157], v150, s[38:39] offset:16
	global_load_dwordx4 v[158:161], v150, s[38:39]
	global_load_dwordx4 v[130:133], v240, s[36:37] offset:144
	global_load_dwordx4 v[134:137], v240, s[36:37] offset:128
	global_load_dwordx4 v[146:149], v150, s[38:39] offset:144
	s_nop 0
	global_load_dwordx4 v[150:153], v150, s[38:39] offset:128
	v_lshlrev_b32_e32 v170, 1, v170
	v_lshl_add_u64 v[220:221], s[34:35], 0, v[170:171]
	v_cndmask_b32_e32 v245, 1.0, v242, vcc
	s_mov_b64 s[34:35], 0
	s_waitcnt vmcnt(4)
	v_pk_fma_f32 v[222:223], v[128:129], v[216:217], v[160:161] op_sel_hi:[1,0,1]
	v_pk_fma_f32 v[224:225], v[126:127], v[216:217], v[158:159] op_sel_hi:[1,0,1]
	v_pk_mul_f32 v[226:227], v[222:223], v[222:223]
	v_pk_mul_f32 v[228:229], v[224:225], v[224:225]
	s_waitcnt vmcnt(1)
	v_pk_fma_f32 v[248:249], v[114:115], v[216:217], v[146:147] op_sel_hi:[1,0,1]
	v_pk_mov_b32 v[230:231], v[228:229], v[226:227] op_sel:[1,0]
	v_mov_b32_e32 v229, v227
	v_pk_add_f32 v[226:227], v[230:231], v[228:229]
	v_pk_fma_f32 v[228:229], v[124:125], v[216:217], v[156:157] op_sel_hi:[1,0,1]
	v_pk_fma_f32 v[230:231], v[122:123], v[216:217], v[154:155] op_sel_hi:[1,0,1]
	v_pk_mul_f32 v[232:233], v[228:229], v[228:229]
	v_pk_mul_f32 v[234:235], v[230:231], v[230:231]
	v_mul_f32_e32 v170, v248, v248
	v_pk_mov_b32 v[236:237], v[234:235], v[232:233] op_sel:[1,0]
	v_mov_b32_e32 v235, v233
	v_pk_add_f32 v[232:233], v[236:237], v[234:235]
	s_waitcnt vmcnt(0)
	v_pk_fma_f32 v[236:237], v[118:119], v[216:217], v[150:151] op_sel_hi:[1,0,1]
	v_mul_f32_e32 v250, v249, v249
	v_pk_add_f32 v[226:227], v[226:227], v[226:227] op_sel:[0,1] op_sel_hi:[1,0]
	v_pk_add_f32 v[232:233], v[232:233], v[232:233] op_sel:[0,1] op_sel_hi:[1,0]
	v_pk_fma_f32 v[234:235], v[120:121], v[216:217], v[152:153] op_sel_hi:[1,0,1]
	v_pk_fma_f32 v[246:247], v[116:117], v[216:217], v[148:149] op_sel_hi:[1,0,1]
	v_mov_b32_e32 v227, v170
	v_mov_b32_e32 v233, v250
	v_mul_f32_e32 v170, v237, v237
	v_mul_f32_e32 v251, v246, v246
	v_pk_add_f32 v[226:227], v[226:227], v[232:233]
	v_pk_fma_f32 v[232:233], v[236:237], v[236:237], v[170:171] op_sel_hi:[1,1,0]
	v_mul_f32_e32 v170, v235, v235
	v_mul_f32_e32 v252, v247, v247
	v_mov_b32_e32 v233, v251
	v_pk_fma_f32 v[250:251], v[234:235], v[234:235], v[170:171] op_sel_hi:[1,1,0]
	s_nop 0
	v_mov_b32_e32 v251, v252
	v_pk_add_f32 v[232:233], v[232:233], v[250:251]
	s_nop 0
	v_pk_add_f32 v[226:227], v[226:227], v[232:233]
	s_nop 0
	v_add_f32_e32 v170, v226, v227
	v_mov_b32_e32 v254, v170
	v_mov_b32_e32 v226, v170
	s_nop 1
	v_permlane16_swap_b32_e32 v254, v226
	s_nop 0
	v_add_f32_e32 v170, v254, v226
	v_mov_b32_e32 v254, v170
	v_mov_b32_e32 v226, v170
	s_nop 1
	v_permlane32_swap_b32_e32 v254, v226
	s_nop 0
	v_add_f32_e32 v170, v254, v226
	v_fmamk_f32 v170, v170, 0x3c800000, v239
	v_rsq_f32_e32 v170, v170
	v_lshl_add_u64 v[226:227], v[220:221], 0, v[218:219]
	v_mul_f32_e32 v170, v245, v170
	v_pk_mul_f32 v[224:225], v[224:225], v[170:171] op_sel_hi:[1,0]
	v_pk_mul_f32 v[222:223], v[222:223], v[170:171] op_sel_hi:[1,0]
	v_pk_mul_f32 v[228:229], v[228:229], v[170:171] op_sel_hi:[1,0]
	v_pk_mul_f32 v[232:233], v[144:145], v[222:223]
	v_pk_mul_f32 v[222:223], v[142:143], v[224:225]
	v_pk_mul_f32 v[224:225], v[230:231], v[170:171] op_sel_hi:[1,0]
	v_pk_mul_f32 v[228:229], v[140:141], v[228:229]
	v_pk_mul_f32 v[224:225], v[138:139], v[224:225]
	v_cvt_pk_bf16_f32 v222, v222, v223
	v_cvt_pk_bf16_f32 v223, v232, v233
	v_cvt_pk_bf16_f32 v224, v224, v225
	v_cvt_pk_bf16_f32 v225, v228, v229
	global_store_dwordx4 v[226:227], v[222:225], off
	v_pk_mul_f32 v[228:229], v[248:249], v[170:171] op_sel_hi:[1,0]
	v_pk_mul_f32 v[230:231], v[246:247], v[170:171] op_sel_hi:[1,0]
	v_pk_mul_f32 v[222:223], v[236:237], v[170:171] op_sel_hi:[1,0]
	v_pk_mul_f32 v[224:225], v[234:235], v[170:171] op_sel_hi:[1,0]
	v_pk_mul_f32 v[222:223], v[134:135], v[222:223]
	v_pk_mul_f32 v[224:225], v[136:137], v[224:225]
	v_pk_mul_f32 v[230:231], v[132:133], v[230:231]
	v_pk_mul_f32 v[228:229], v[130:131], v[228:229]
	v_cvt_pk_bf16_f32 v222, v222, v223
	v_cvt_pk_bf16_f32 v223, v224, v225
	v_cvt_pk_bf16_f32 v224, v228, v229
	v_cvt_pk_bf16_f32 v225, v230, v231
	global_store_dwordx4 v[226:227], v[222:225], off offset:64
	v_pk_fma_f32 v[236:237], v[98:99], v[212:213], v[146:147] op_sel_hi:[1,0,1]
	s_nop 0
	v_pk_fma_f32 v[222:223], v[112:113], v[212:213], v[160:161] op_sel_hi:[1,0,1]
	v_pk_fma_f32 v[224:225], v[110:111], v[212:213], v[158:159] op_sel_hi:[1,0,1]
	v_pk_mul_f32 v[226:227], v[222:223], v[222:223]
	v_pk_mul_f32 v[228:229], v[224:225], v[224:225]
	v_mul_f32_e32 v170, v236, v236
	v_pk_mov_b32 v[230:231], v[228:229], v[226:227] op_sel:[1,0]
	v_mov_b32_e32 v229, v227
	v_pk_add_f32 v[246:247], v[230:231], v[228:229]
	v_pk_fma_f32 v[226:227], v[108:109], v[212:213], v[156:157] op_sel_hi:[1,0,1]
	v_pk_fma_f32 v[228:229], v[106:107], v[212:213], v[154:155] op_sel_hi:[1,0,1]
; __device__ __forceinline__ unsigned cvt_pk_bf16(float lo, float hi) { f32x2_t v = {lo, hi}; bf16x2_t b = __builtin_convertvector(v, bf16x2_t); return __builtin_bit_cast(unsigned, b); }
;     __device__ __forceinline__ void operator()(const f32x4 (&acc)[2][2][4][2], const Unit& u, int wr, int wc, int fr, int fq) const {
;     ...
;                 for (int m = 0; m < 4; ++m) {
;                     f32x4 v[2][2]; float ss = 0.f;
; #pragma unroll
;                     for (int bj = 0; bj < 2; ++bj)
; #pragma unroll
;                         for (int n = 0; n < 2; ++n) { v[bj][n] = acc[ai][bj][m][n] * rs[ai][m] + s4[bj][n]; const f32x4 t = v[bj][n]; ss += (t[0] * t[0] + t[1] * t[1]) + (t[2] * t[2] + t[3] * t[3]); }
;                     ss += __shfl_xor(ss, 16); ss += __shfl_xor(ss, 32);
;                     const float rq = __builtin_amdgcn_rsqf(ss * (1.0f / 64.0f) + EPS) * sc;
;                     bf16_t* rowp = O + (size_t)(row0 + ai * HALF + m * 16) * D + col0;
; #pragma unroll
;                     for (int bj = 0; bj < 2; ++bj) { const f32x4 v0 = v[bj][0] * rq * w4[bj][0], v1 = v[bj][1] * rq * w4[bj][1];
;                         u32x4 w; w.x = cvt_pk_bf16(v0[0], v0[1]); w.y = cvt_pk_bf16(v0[2], v0[3]); w.z = cvt_pk_bf16(v1[0], v1[1]); w.w = cvt_pk_bf16(v1[2], v1[3]);
;                         *(u32x4*)(rowp + 32 * bj) = w; } }
	v_pk_mul_f32 v[230:231], v[226:227], v[226:227]
	v_pk_mul_f32 v[232:233], v[228:229], v[228:229]
	v_mul_f32_e32 v250, v237, v237
	v_pk_mov_b32 v[234:235], v[232:233], v[230:231] op_sel:[1,0]
	v_mov_b32_e32 v233, v231
	v_pk_add_f32 v[248:249], v[234:235], v[232:233]
	v_pk_fma_f32 v[232:233], v[102:103], v[212:213], v[150:151] op_sel_hi:[1,0,1]
	v_pk_add_f32 v[246:247], v[246:247], v[246:247] op_sel:[0,1] op_sel_hi:[1,0]
	v_pk_add_f32 v[248:249], v[248:249], v[248:249] op_sel:[0,1] op_sel_hi:[1,0]
	v_pk_fma_f32 v[230:231], v[104:105], v[212:213], v[152:153] op_sel_hi:[1,0,1]
	v_pk_fma_f32 v[234:235], v[100:101], v[212:213], v[148:149] op_sel_hi:[1,0,1]
	v_mov_b32_e32 v247, v170
	v_mov_b32_e32 v249, v250
	v_mul_f32_e32 v170, v233, v233
	v_mul_f32_e32 v251, v234, v234
	v_pk_add_f32 v[246:247], v[246:247], v[248:249]
	v_pk_fma_f32 v[248:249], v[232:233], v[232:233], v[170:171] op_sel_hi:[1,1,0]
	v_mul_f32_e32 v170, v231, v231
	v_mul_f32_e32 v252, v235, v235
	v_mov_b32_e32 v249, v251
	v_pk_fma_f32 v[250:251], v[230:231], v[230:231], v[170:171] op_sel_hi:[1,1,0]
	s_nop 0
	v_mov_b32_e32 v251, v252
	v_pk_add_f32 v[248:249], v[248:249], v[250:251]
	s_nop 0
	v_pk_add_f32 v[246:247], v[246:247], v[248:249]
	s_nop 0
	v_add_f32_e32 v170, v246, v247
	v_mov_b32_e32 v254, v170
	v_mov_b32_e32 v246, v170
	s_nop 1
	v_permlane16_swap_b32_e32 v254, v246
	s_nop 0
	v_add_f32_e32 v170, v254, v246
	v_mov_b32_e32 v254, v170
	v_mov_b32_e32 v246, v170
	s_nop 1
	v_permlane32_swap_b32_e32 v254, v246
	s_nop 0
	v_add_f32_e32 v170, v254, v246
	v_fmamk_f32 v170, v170, 0x3c800000, v239
	v_rsq_f32_e32 v170, v170
	v_lshl_add_u64 v[246:247], v[220:221], 0, v[214:215]
	v_mul_f32_e32 v170, v245, v170
	v_pk_mul_f32 v[224:225], v[224:225], v[170:171] op_sel_hi:[1,0]
	v_pk_mul_f32 v[222:223], v[222:223], v[170:171] op_sel_hi:[1,0]
	v_pk_mul_f32 v[226:227], v[226:227], v[170:171] op_sel_hi:[1,0]
	v_pk_mul_f32 v[248:249], v[144:145], v[222:223]
	v_pk_mul_f32 v[222:223], v[142:143], v[224:225]
	v_pk_mul_f32 v[224:225], v[228:229], v[170:171] op_sel_hi:[1,0]
	v_pk_mul_f32 v[226:227], v[140:141], v[226:227]
	v_pk_mul_f32 v[224:225], v[138:139], v[224:225]
	v_cvt_pk_bf16_f32 v222, v222, v223
	v_cvt_pk_bf16_f32 v223, v248, v249
	v_cvt_pk_bf16_f32 v224, v224, v225
	v_cvt_pk_bf16_f32 v225, v226, v227
	global_store_dwordx4 v[246:247], v[222:225], off
	v_pk_mul_f32 v[226:227], v[236:237], v[170:171] op_sel_hi:[1,0]
	v_pk_mul_f32 v[228:229], v[234:235], v[170:171] op_sel_hi:[1,0]
	v_pk_mul_f32 v[222:223], v[232:233], v[170:171] op_sel_hi:[1,0]
	v_pk_mul_f32 v[224:225], v[230:231], v[170:171] op_sel_hi:[1,0]
	v_pk_mul_f32 v[222:223], v[134:135], v[222:223]
	v_pk_mul_f32 v[224:225], v[136:137], v[224:225]
	v_pk_mul_f32 v[228:229], v[132:133], v[228:229]
	v_pk_mul_f32 v[226:227], v[130:131], v[226:227]
	v_cvt_pk_bf16_f32 v222, v222, v223
	v_cvt_pk_bf16_f32 v223, v224, v225
	v_cvt_pk_bf16_f32 v224, v226, v227
	v_cvt_pk_bf16_f32 v225, v228, v229
	global_store_dwordx4 v[246:247], v[222:225], off offset:64
	v_pk_fma_f32 v[248:249], v[82:83], v[208:209], v[146:147] op_sel_hi:[1,0,1]
	v_pk_fma_f32 v[246:247], v[84:85], v[208:209], v[148:149] op_sel_hi:[1,0,1]
	v_pk_fma_f32 v[222:223], v[96:97], v[208:209], v[160:161] op_sel_hi:[1,0,1]
	v_pk_fma_f32 v[224:225], v[94:95], v[208:209], v[158:159] op_sel_hi:[1,0,1]
	v_pk_mul_f32 v[226:227], v[222:223], v[222:223]
	v_pk_mul_f32 v[228:229], v[224:225], v[224:225]
	v_mul_f32_e32 v170, v248, v248
	v_pk_mov_b32 v[230:231], v[228:229], v[226:227] op_sel:[1,0]
	v_mov_b32_e32 v229, v227
	v_pk_add_f32 v[226:227], v[230:231], v[228:229]
	v_pk_fma_f32 v[228:229], v[92:93], v[208:209], v[156:157] op_sel_hi:[1,0,1]
	v_pk_fma_f32 v[230:231], v[90:91], v[208:209], v[154:155] op_sel_hi:[1,0,1]
	v_pk_mul_f32 v[232:233], v[228:229], v[228:229]
	v_pk_mul_f32 v[234:235], v[230:231], v[230:231]
	v_mul_f32_e32 v250, v249, v249
	v_pk_mov_b32 v[236:237], v[234:235], v[232:233] op_sel:[1,0]
	v_mov_b32_e32 v235, v233
	v_pk_add_f32 v[232:233], v[236:237], v[234:235]
	v_pk_fma_f32 v[236:237], v[86:87], v[208:209], v[150:151] op_sel_hi:[1,0,1]
	v_pk_add_f32 v[226:227], v[226:227], v[226:227] op_sel:[0,1] op_sel_hi:[1,0]
	v_pk_add_f32 v[232:233], v[232:233], v[232:233] op_sel:[0,1] op_sel_hi:[1,0]
	v_pk_fma_f32 v[234:235], v[88:89], v[208:209], v[152:153] op_sel_hi:[1,0,1]
	v_mov_b32_e32 v227, v170
	v_mov_b32_e32 v233, v250
	v_mul_f32_e32 v170, v237, v237
	v_mul_f32_e32 v251, v246, v246
	v_pk_add_f32 v[226:227], v[226:227], v[232:233]
	v_pk_fma_f32 v[232:233], v[236:237], v[236:237], v[170:171] op_sel_hi:[1,1,0]
	v_mul_f32_e32 v170, v235, v235
	v_mul_f32_e32 v252, v247, v247
	v_mov_b32_e32 v233, v251
	v_pk_fma_f32 v[250:251], v[234:235], v[234:235], v[170:171] op_sel_hi:[1,1,0]
	s_nop 0
	v_mov_b32_e32 v251, v252
	v_pk_add_f32 v[232:233], v[232:233], v[250:251]
	s_nop 0
	v_pk_add_f32 v[226:227], v[226:227], v[232:233]
	s_nop 0
	v_add_f32_e32 v170, v226, v227
	v_mov_b32_e32 v254, v170
	v_mov_b32_e32 v226, v170
	s_nop 1
	v_permlane16_swap_b32_e32 v254, v226
	s_nop 0
	v_add_f32_e32 v170, v254, v226
	v_mov_b32_e32 v254, v170
	v_mov_b32_e32 v226, v170
	s_nop 1
	v_permlane32_swap_b32_e32 v254, v226
	s_nop 0
	v_add_f32_e32 v170, v254, v226
	v_fmamk_f32 v170, v170, 0x3c800000, v239
	v_rsq_f32_e32 v170, v170
	v_lshl_add_u64 v[226:227], v[220:221], 0, v[210:211]
	v_mul_f32_e32 v170, v245, v170
	v_pk_mul_f32 v[224:225], v[224:225], v[170:171] op_sel_hi:[1,0]
	v_pk_mul_f32 v[222:223], v[222:223], v[170:171] op_sel_hi:[1,0]
	v_pk_mul_f32 v[228:229], v[228:229], v[170:171] op_sel_hi:[1,0]
	v_pk_mul_f32 v[232:233], v[144:145], v[222:223]
	v_pk_mul_f32 v[222:223], v[142:143], v[224:225]
; __device__ __forceinline__ unsigned cvt_pk_bf16(float lo, float hi) { f32x2_t v = {lo, hi}; bf16x2_t b = __builtin_convertvector(v, bf16x2_t); return __builtin_bit_cast(unsigned, b); }
;     __device__ __forceinline__ void operator()(const f32x4 (&acc)[2][2][4][2], const Unit& u, int wr, int wc, int fr, int fq) const {
;     ...
;                 for (int m = 0; m < 4; ++m) {
;                     f32x4 v[2][2]; float ss = 0.f;
; #pragma unroll
;                     for (int bj = 0; bj < 2; ++bj)
; #pragma unroll
;                         for (int n = 0; n < 2; ++n) { v[bj][n] = acc[ai][bj][m][n] * rs[ai][m] + s4[bj][n]; const f32x4 t = v[bj][n]; ss += (t[0] * t[0] + t[1] * t[1]) + (t[2] * t[2] + t[3] * t[3]); }
;                     ss += __shfl_xor(ss, 16); ss += __shfl_xor(ss, 32);
;                     const float rq = __builtin_amdgcn_rsqf(ss * (1.0f / 64.0f) + EPS) * sc;
;                     bf16_t* rowp = O + (size_t)(row0 + ai * HALF + m * 16) * D + col0;
; #pragma unroll
;                     for (int bj = 0; bj < 2; ++bj) { const f32x4 v0 = v[bj][0] * rq * w4[bj][0], v1 = v[bj][1] * rq * w4[bj][1];
;                         u32x4 w; w.x = cvt_pk_bf16(v0[0], v0[1]); w.y = cvt_pk_bf16(v0[2], v0[3]); w.z = cvt_pk_bf16(v1[0], v1[1]); w.w = cvt_pk_bf16(v1[2], v1[3]);
;                         *(u32x4*)(rowp + 32 * bj) = w; } }
	v_pk_mul_f32 v[224:225], v[230:231], v[170:171] op_sel_hi:[1,0]
	v_pk_mul_f32 v[228:229], v[140:141], v[228:229]
	v_pk_mul_f32 v[224:225], v[138:139], v[224:225]
	v_cvt_pk_bf16_f32 v222, v222, v223
	v_cvt_pk_bf16_f32 v223, v232, v233
	v_cvt_pk_bf16_f32 v224, v224, v225
	v_cvt_pk_bf16_f32 v225, v228, v229
	global_store_dwordx4 v[226:227], v[222:225], off
	v_pk_mul_f32 v[228:229], v[248:249], v[170:171] op_sel_hi:[1,0]
	v_pk_mul_f32 v[230:231], v[246:247], v[170:171] op_sel_hi:[1,0]
	v_pk_mul_f32 v[222:223], v[236:237], v[170:171] op_sel_hi:[1,0]
	v_pk_mul_f32 v[224:225], v[234:235], v[170:171] op_sel_hi:[1,0]
	v_pk_mul_f32 v[222:223], v[134:135], v[222:223]
	v_pk_mul_f32 v[224:225], v[136:137], v[224:225]
	v_pk_mul_f32 v[230:231], v[132:133], v[230:231]
	v_pk_mul_f32 v[228:229], v[130:131], v[228:229]
	v_cvt_pk_bf16_f32 v222, v222, v223
	v_cvt_pk_bf16_f32 v223, v224, v225
	v_cvt_pk_bf16_f32 v224, v228, v229
	v_cvt_pk_bf16_f32 v225, v230, v231
	global_store_dwordx4 v[226:227], v[222:225], off offset:64
	v_pk_fma_f32 v[248:249], v[66:67], v[204:205], v[146:147] op_sel_hi:[1,0,1]
	v_pk_fma_f32 v[246:247], v[68:69], v[204:205], v[148:149] op_sel_hi:[1,0,1]
	v_pk_fma_f32 v[222:223], v[80:81], v[204:205], v[160:161] op_sel_hi:[1,0,1]
	v_pk_fma_f32 v[224:225], v[78:79], v[204:205], v[158:159] op_sel_hi:[1,0,1]
	v_pk_mul_f32 v[226:227], v[222:223], v[222:223]
	v_pk_mul_f32 v[228:229], v[224:225], v[224:225]
	v_mul_f32_e32 v170, v248, v248
	v_pk_mov_b32 v[230:231], v[228:229], v[226:227] op_sel:[1,0]
	v_mov_b32_e32 v229, v227
	v_pk_add_f32 v[226:227], v[230:231], v[228:229]
	v_pk_fma_f32 v[228:229], v[76:77], v[204:205], v[156:157] op_sel_hi:[1,0,1]
	v_pk_fma_f32 v[230:231], v[74:75], v[204:205], v[154:155] op_sel_hi:[1,0,1]
	v_pk_mul_f32 v[232:233], v[228:229], v[228:229]
	v_pk_mul_f32 v[234:235], v[230:231], v[230:231]
	v_mul_f32_e32 v250, v249, v249
	v_pk_mov_b32 v[236:237], v[234:235], v[232:233] op_sel:[1,0]
	v_mov_b32_e32 v235, v233
	v_pk_add_f32 v[232:233], v[236:237], v[234:235]
	v_pk_fma_f32 v[236:237], v[70:71], v[204:205], v[150:151] op_sel_hi:[1,0,1]
	v_pk_add_f32 v[226:227], v[226:227], v[226:227] op_sel:[0,1] op_sel_hi:[1,0]
	v_pk_add_f32 v[232:233], v[232:233], v[232:233] op_sel:[0,1] op_sel_hi:[1,0]
	v_pk_fma_f32 v[234:235], v[72:73], v[204:205], v[152:153] op_sel_hi:[1,0,1]
	v_mov_b32_e32 v227, v170
	v_mov_b32_e32 v233, v250
	v_mul_f32_e32 v170, v237, v237
	v_mul_f32_e32 v251, v246, v246
	v_pk_add_f32 v[226:227], v[226:227], v[232:233]
	v_pk_fma_f32 v[232:233], v[236:237], v[236:237], v[170:171] op_sel_hi:[1,1,0]
	v_mul_f32_e32 v170, v235, v235
	v_mul_f32_e32 v252, v247, v247
	v_mov_b32_e32 v233, v251
	v_pk_fma_f32 v[250:251], v[234:235], v[234:235], v[170:171] op_sel_hi:[1,1,0]
	s_nop 0
	v_mov_b32_e32 v251, v252
	v_pk_add_f32 v[232:233], v[232:233], v[250:251]
	s_nop 0
	v_pk_add_f32 v[226:227], v[226:227], v[232:233]
	s_nop 0
	v_add_f32_e32 v170, v226, v227
	v_mov_b32_e32 v254, v170
	v_mov_b32_e32 v226, v170
	s_nop 1
	v_permlane16_swap_b32_e32 v254, v226
	s_nop 0
	v_add_f32_e32 v170, v254, v226
	v_mov_b32_e32 v254, v170
	v_mov_b32_e32 v226, v170
	s_nop 1
	v_permlane32_swap_b32_e32 v254, v226
	s_nop 0
	v_add_f32_e32 v170, v254, v226
	v_fmamk_f32 v170, v170, 0x3c800000, v239
	v_rsq_f32_e32 v170, v170
	v_lshl_add_u64 v[226:227], v[220:221], 0, v[206:207]
	v_mul_f32_e32 v170, v245, v170
	v_pk_mul_f32 v[224:225], v[224:225], v[170:171] op_sel_hi:[1,0]
	v_pk_mul_f32 v[222:223], v[222:223], v[170:171] op_sel_hi:[1,0]
	v_pk_mul_f32 v[228:229], v[228:229], v[170:171] op_sel_hi:[1,0]
	v_pk_mul_f32 v[232:233], v[144:145], v[222:223]
	v_pk_mul_f32 v[222:223], v[142:143], v[224:225]
	v_pk_mul_f32 v[224:225], v[230:231], v[170:171] op_sel_hi:[1,0]
	v_pk_mul_f32 v[228:229], v[140:141], v[228:229]
	v_pk_mul_f32 v[224:225], v[138:139], v[224:225]
	v_cvt_pk_bf16_f32 v222, v222, v223
	v_cvt_pk_bf16_f32 v223, v232, v233
	v_cvt_pk_bf16_f32 v224, v224, v225
	v_cvt_pk_bf16_f32 v225, v228, v229
	global_store_dwordx4 v[226:227], v[222:225], off
	v_pk_mul_f32 v[228:229], v[248:249], v[170:171] op_sel_hi:[1,0]
	v_pk_mul_f32 v[230:231], v[246:247], v[170:171] op_sel_hi:[1,0]
	v_pk_mul_f32 v[222:223], v[236:237], v[170:171] op_sel_hi:[1,0]
	v_pk_mul_f32 v[224:225], v[234:235], v[170:171] op_sel_hi:[1,0]
	v_pk_mul_f32 v[222:223], v[134:135], v[222:223]
	v_pk_mul_f32 v[224:225], v[136:137], v[224:225]
	v_pk_mul_f32 v[230:231], v[132:133], v[230:231]
	v_pk_mul_f32 v[228:229], v[130:131], v[228:229]
	v_cvt_pk_bf16_f32 v222, v222, v223
	v_cvt_pk_bf16_f32 v223, v224, v225
	v_cvt_pk_bf16_f32 v224, v228, v229
	v_cvt_pk_bf16_f32 v225, v230, v231
	global_store_dwordx4 v[226:227], v[222:225], off offset:64
	v_pk_fma_f32 v[248:249], v[50:51], v[200:201], v[146:147] op_sel_hi:[1,0,1]
	v_pk_fma_f32 v[246:247], v[52:53], v[200:201], v[148:149] op_sel_hi:[1,0,1]
	v_pk_fma_f32 v[222:223], v[64:65], v[200:201], v[160:161] op_sel_hi:[1,0,1]
	v_pk_fma_f32 v[224:225], v[62:63], v[200:201], v[158:159] op_sel_hi:[1,0,1]
	v_pk_mul_f32 v[226:227], v[222:223], v[222:223]
	v_pk_mul_f32 v[228:229], v[224:225], v[224:225]
	v_mul_f32_e32 v170, v248, v248
	v_pk_mov_b32 v[230:231], v[228:229], v[226:227] op_sel:[1,0]
	v_mov_b32_e32 v229, v227
	v_pk_add_f32 v[226:227], v[230:231], v[228:229]
	v_pk_fma_f32 v[228:229], v[60:61], v[200:201], v[156:157] op_sel_hi:[1,0,1]
	v_pk_fma_f32 v[230:231], v[58:59], v[200:201], v[154:155] op_sel_hi:[1,0,1]
	v_pk_mul_f32 v[232:233], v[228:229], v[228:229]
	v_pk_mul_f32 v[234:235], v[230:231], v[230:231]
	v_mul_f32_e32 v250, v249, v249
	v_pk_mov_b32 v[236:237], v[234:235], v[232:233] op_sel:[1,0]
	v_mov_b32_e32 v235, v233
	v_pk_add_f32 v[232:233], v[236:237], v[234:235]
; __device__ __forceinline__ unsigned cvt_pk_bf16(float lo, float hi) { f32x2_t v = {lo, hi}; bf16x2_t b = __builtin_convertvector(v, bf16x2_t); return __builtin_bit_cast(unsigned, b); }
;     __device__ __forceinline__ void operator()(const f32x4 (&acc)[2][2][4][2], const Unit& u, int wr, int wc, int fr, int fq) const {
;     ...
;                 for (int m = 0; m < 4; ++m) {
;                     f32x4 v[2][2]; float ss = 0.f;
; #pragma unroll
;                     for (int bj = 0; bj < 2; ++bj)
; #pragma unroll
;                         for (int n = 0; n < 2; ++n) { v[bj][n] = acc[ai][bj][m][n] * rs[ai][m] + s4[bj][n]; const f32x4 t = v[bj][n]; ss += (t[0] * t[0] + t[1] * t[1]) + (t[2] * t[2] + t[3] * t[3]); }
;                     ss += __shfl_xor(ss, 16); ss += __shfl_xor(ss, 32);
;                     const float rq = __builtin_amdgcn_rsqf(ss * (1.0f / 64.0f) + EPS) * sc;
;                     bf16_t* rowp = O + (size_t)(row0 + ai * HALF + m * 16) * D + col0;
; #pragma unroll
;                     for (int bj = 0; bj < 2; ++bj) { const f32x4 v0 = v[bj][0] * rq * w4[bj][0], v1 = v[bj][1] * rq * w4[bj][1];
;                         u32x4 w; w.x = cvt_pk_bf16(v0[0], v0[1]); w.y = cvt_pk_bf16(v0[2], v0[3]); w.z = cvt_pk_bf16(v1[0], v1[1]); w.w = cvt_pk_bf16(v1[2], v1[3]);
;                         *(u32x4*)(rowp + 32 * bj) = w; } }
	v_pk_fma_f32 v[236:237], v[54:55], v[200:201], v[150:151] op_sel_hi:[1,0,1]
	v_pk_add_f32 v[226:227], v[226:227], v[226:227] op_sel:[0,1] op_sel_hi:[1,0]
	v_pk_add_f32 v[232:233], v[232:233], v[232:233] op_sel:[0,1] op_sel_hi:[1,0]
	v_pk_fma_f32 v[234:235], v[56:57], v[200:201], v[152:153] op_sel_hi:[1,0,1]
	v_mov_b32_e32 v227, v170
	v_mov_b32_e32 v233, v250
	v_mul_f32_e32 v170, v237, v237
	v_mul_f32_e32 v251, v246, v246
	v_pk_add_f32 v[226:227], v[226:227], v[232:233]
	v_pk_fma_f32 v[232:233], v[236:237], v[236:237], v[170:171] op_sel_hi:[1,1,0]
	v_mul_f32_e32 v170, v235, v235
	v_mul_f32_e32 v252, v247, v247
	v_mov_b32_e32 v233, v251
	v_pk_fma_f32 v[250:251], v[234:235], v[234:235], v[170:171] op_sel_hi:[1,1,0]
	s_nop 0
	v_mov_b32_e32 v251, v252
	v_pk_add_f32 v[232:233], v[232:233], v[250:251]
	s_nop 0
	v_pk_add_f32 v[226:227], v[226:227], v[232:233]
	s_nop 0
	v_add_f32_e32 v170, v226, v227
	v_mov_b32_e32 v254, v170
	v_mov_b32_e32 v226, v170
	s_nop 1
	v_permlane16_swap_b32_e32 v254, v226
	s_nop 0
	v_add_f32_e32 v170, v254, v226
	v_mov_b32_e32 v254, v170
	v_mov_b32_e32 v226, v170
	s_nop 1
	v_permlane32_swap_b32_e32 v254, v226
	s_nop 0
	v_add_f32_e32 v170, v254, v226
	v_fmamk_f32 v170, v170, 0x3c800000, v239
	v_rsq_f32_e32 v170, v170
	v_lshl_add_u64 v[226:227], v[220:221], 0, v[202:203]
	v_mul_f32_e32 v170, v245, v170
	v_pk_mul_f32 v[224:225], v[224:225], v[170:171] op_sel_hi:[1,0]
	v_pk_mul_f32 v[222:223], v[222:223], v[170:171] op_sel_hi:[1,0]
	v_pk_mul_f32 v[228:229], v[228:229], v[170:171] op_sel_hi:[1,0]
	v_pk_mul_f32 v[232:233], v[144:145], v[222:223]
	v_pk_mul_f32 v[222:223], v[142:143], v[224:225]
	v_pk_mul_f32 v[224:225], v[230:231], v[170:171] op_sel_hi:[1,0]
	v_pk_mul_f32 v[228:229], v[140:141], v[228:229]
	v_pk_mul_f32 v[224:225], v[138:139], v[224:225]
	v_cvt_pk_bf16_f32 v222, v222, v223
	v_cvt_pk_bf16_f32 v223, v232, v233
	v_cvt_pk_bf16_f32 v224, v224, v225
	v_cvt_pk_bf16_f32 v225, v228, v229
	global_store_dwordx4 v[226:227], v[222:225], off
	v_pk_mul_f32 v[228:229], v[248:249], v[170:171] op_sel_hi:[1,0]
	v_pk_mul_f32 v[230:231], v[246:247], v[170:171] op_sel_hi:[1,0]
	v_pk_mul_f32 v[222:223], v[236:237], v[170:171] op_sel_hi:[1,0]
	v_pk_mul_f32 v[224:225], v[234:235], v[170:171] op_sel_hi:[1,0]
	v_pk_mul_f32 v[222:223], v[134:135], v[222:223]
	v_pk_mul_f32 v[224:225], v[136:137], v[224:225]
	v_pk_mul_f32 v[230:231], v[132:133], v[230:231]
	v_pk_mul_f32 v[228:229], v[130:131], v[228:229]
	v_cvt_pk_bf16_f32 v222, v222, v223
	v_cvt_pk_bf16_f32 v223, v224, v225
	v_cvt_pk_bf16_f32 v224, v228, v229
	v_cvt_pk_bf16_f32 v225, v230, v231
	global_store_dwordx4 v[226:227], v[222:225], off offset:64
	v_pk_fma_f32 v[248:249], v[34:35], v[198:199], v[146:147] op_sel_hi:[1,0,1]
	v_pk_fma_f32 v[246:247], v[36:37], v[198:199], v[148:149] op_sel_hi:[1,0,1]
	v_pk_fma_f32 v[222:223], v[48:49], v[198:199], v[160:161] op_sel_hi:[1,0,1]
	v_pk_fma_f32 v[224:225], v[46:47], v[198:199], v[158:159] op_sel_hi:[1,0,1]
	v_pk_mul_f32 v[226:227], v[222:223], v[222:223]
	v_pk_mul_f32 v[228:229], v[224:225], v[224:225]
	v_mul_f32_e32 v170, v248, v248
	v_pk_mov_b32 v[230:231], v[228:229], v[226:227] op_sel:[1,0]
	v_mov_b32_e32 v229, v227
	v_pk_add_f32 v[226:227], v[230:231], v[228:229]
	v_pk_fma_f32 v[228:229], v[44:45], v[198:199], v[156:157] op_sel_hi:[1,0,1]
	v_pk_fma_f32 v[230:231], v[42:43], v[198:199], v[154:155] op_sel_hi:[1,0,1]
	v_pk_mul_f32 v[232:233], v[228:229], v[228:229]
	v_pk_mul_f32 v[234:235], v[230:231], v[230:231]
	v_mul_f32_e32 v250, v249, v249
	v_pk_mov_b32 v[236:237], v[234:235], v[232:233] op_sel:[1,0]
	v_mov_b32_e32 v235, v233
	v_pk_add_f32 v[232:233], v[236:237], v[234:235]
	v_pk_fma_f32 v[236:237], v[38:39], v[198:199], v[150:151] op_sel_hi:[1,0,1]
	v_pk_add_f32 v[226:227], v[226:227], v[226:227] op_sel:[0,1] op_sel_hi:[1,0]
	v_pk_add_f32 v[232:233], v[232:233], v[232:233] op_sel:[0,1] op_sel_hi:[1,0]
	v_pk_fma_f32 v[234:235], v[40:41], v[198:199], v[152:153] op_sel_hi:[1,0,1]
	v_mov_b32_e32 v227, v170
	v_mov_b32_e32 v233, v250
	v_mul_f32_e32 v170, v237, v237
	v_mul_f32_e32 v251, v246, v246
	v_pk_add_f32 v[226:227], v[226:227], v[232:233]
	v_pk_fma_f32 v[232:233], v[236:237], v[236:237], v[170:171] op_sel_hi:[1,1,0]
	v_mul_f32_e32 v170, v235, v235
	v_mul_f32_e32 v252, v247, v247
	v_mov_b32_e32 v233, v251
	v_pk_fma_f32 v[250:251], v[234:235], v[234:235], v[170:171] op_sel_hi:[1,1,0]
	s_nop 0
	v_mov_b32_e32 v251, v252
	v_pk_add_f32 v[232:233], v[232:233], v[250:251]
	s_nop 0
	v_pk_add_f32 v[226:227], v[226:227], v[232:233]
	s_nop 0
	v_add_f32_e32 v170, v226, v227
	v_mov_b32_e32 v254, v170
	v_mov_b32_e32 v226, v170
	s_nop 1
	v_permlane16_swap_b32_e32 v254, v226
	s_nop 0
	v_add_f32_e32 v170, v254, v226
	v_mov_b32_e32 v254, v170
	v_mov_b32_e32 v226, v170
	s_nop 1
	v_permlane32_swap_b32_e32 v254, v226
	s_nop 0
	v_add_f32_e32 v170, v254, v226
	v_fmamk_f32 v170, v170, 0x3c800000, v239
	v_rsq_f32_e32 v170, v170
	v_lshlrev_b64 v[226:227], 11, v[182:183]
	v_lshl_add_u64 v[226:227], v[220:221], 0, v[226:227]
	v_mul_f32_e32 v170, v245, v170
	v_pk_mul_f32 v[224:225], v[224:225], v[170:171] op_sel_hi:[1,0]
	v_pk_mul_f32 v[222:223], v[222:223], v[170:171] op_sel_hi:[1,0]
	v_pk_mul_f32 v[228:229], v[228:229], v[170:171] op_sel_hi:[1,0]
	v_pk_mul_f32 v[232:233], v[144:145], v[222:223]
	v_pk_mul_f32 v[222:223], v[142:143], v[224:225]
	v_pk_mul_f32 v[224:225], v[230:231], v[170:171] op_sel_hi:[1,0]
	v_pk_mul_f32 v[228:229], v[140:141], v[228:229]
	v_pk_mul_f32 v[224:225], v[138:139], v[224:225]
	v_cvt_pk_bf16_f32 v222, v222, v223
	v_cvt_pk_bf16_f32 v223, v232, v233
	v_cvt_pk_bf16_f32 v224, v224, v225
	v_cvt_pk_bf16_f32 v225, v228, v229
; __device__ __forceinline__ unsigned cvt_pk_bf16(float lo, float hi) { f32x2_t v = {lo, hi}; bf16x2_t b = __builtin_convertvector(v, bf16x2_t); return __builtin_bit_cast(unsigned, b); }
;     __device__ __forceinline__ void operator()(const f32x4 (&acc)[2][2][4][2], const Unit& u, int wr, int wc, int fr, int fq) const {
;     ...
;                 for (int m = 0; m < 4; ++m) {
;                     f32x4 v[2][2]; float ss = 0.f;
; #pragma unroll
;                     for (int bj = 0; bj < 2; ++bj)
; #pragma unroll
;                         for (int n = 0; n < 2; ++n) { v[bj][n] = acc[ai][bj][m][n] * rs[ai][m] + s4[bj][n]; const f32x4 t = v[bj][n]; ss += (t[0] * t[0] + t[1] * t[1]) + (t[2] * t[2] + t[3] * t[3]); }
;                     ss += __shfl_xor(ss, 16); ss += __shfl_xor(ss, 32);
;                     const float rq = __builtin_amdgcn_rsqf(ss * (1.0f / 64.0f) + EPS) * sc;
;                     bf16_t* rowp = O + (size_t)(row0 + ai * HALF + m * 16) * D + col0;
; #pragma unroll
;                     for (int bj = 0; bj < 2; ++bj) { const f32x4 v0 = v[bj][0] * rq * w4[bj][0], v1 = v[bj][1] * rq * w4[bj][1];
;                         u32x4 w; w.x = cvt_pk_bf16(v0[0], v0[1]); w.y = cvt_pk_bf16(v0[2], v0[3]); w.z = cvt_pk_bf16(v1[0], v1[1]); w.w = cvt_pk_bf16(v1[2], v1[3]);
;                         *(u32x4*)(rowp + 32 * bj) = w; } }
	global_store_dwordx4 v[226:227], v[222:225], off
	v_pk_mul_f32 v[228:229], v[248:249], v[170:171] op_sel_hi:[1,0]
	v_pk_mul_f32 v[230:231], v[246:247], v[170:171] op_sel_hi:[1,0]
	v_pk_mul_f32 v[222:223], v[236:237], v[170:171] op_sel_hi:[1,0]
	v_pk_mul_f32 v[224:225], v[234:235], v[170:171] op_sel_hi:[1,0]
	v_pk_mul_f32 v[222:223], v[134:135], v[222:223]
	v_pk_mul_f32 v[224:225], v[136:137], v[224:225]
	v_pk_mul_f32 v[230:231], v[132:133], v[230:231]
	v_pk_mul_f32 v[228:229], v[130:131], v[228:229]
	v_cvt_pk_bf16_f32 v222, v222, v223
	v_cvt_pk_bf16_f32 v223, v224, v225
	v_cvt_pk_bf16_f32 v224, v228, v229
	v_cvt_pk_bf16_f32 v225, v230, v231
	global_store_dwordx4 v[226:227], v[222:225], off offset:64
	v_pk_fma_f32 v[248:249], v[14:15], v[196:197], v[146:147] op_sel_hi:[1,0,1]
	v_pk_fma_f32 v[246:247], v[16:17], v[196:197], v[148:149] op_sel_hi:[1,0,1]
	v_pk_fma_f32 v[222:223], v[32:33], v[196:197], v[160:161] op_sel_hi:[1,0,1]
	v_pk_fma_f32 v[224:225], v[30:31], v[196:197], v[158:159] op_sel_hi:[1,0,1]
	v_pk_mul_f32 v[226:227], v[222:223], v[222:223]
	v_pk_mul_f32 v[228:229], v[224:225], v[224:225]
	v_mul_f32_e32 v170, v248, v248
	v_pk_mov_b32 v[230:231], v[228:229], v[226:227] op_sel:[1,0]
	v_mov_b32_e32 v229, v227
	v_pk_add_f32 v[226:227], v[230:231], v[228:229]
	v_pk_fma_f32 v[228:229], v[28:29], v[196:197], v[156:157] op_sel_hi:[1,0,1]
	v_pk_fma_f32 v[230:231], v[26:27], v[196:197], v[154:155] op_sel_hi:[1,0,1]
	v_pk_mul_f32 v[232:233], v[228:229], v[228:229]
	v_pk_mul_f32 v[234:235], v[230:231], v[230:231]
	v_mul_f32_e32 v250, v249, v249
	v_pk_mov_b32 v[236:237], v[234:235], v[232:233] op_sel:[1,0]
	v_mov_b32_e32 v235, v233
	v_pk_add_f32 v[232:233], v[236:237], v[234:235]
	v_pk_fma_f32 v[236:237], v[18:19], v[196:197], v[150:151] op_sel_hi:[1,0,1]
	v_pk_add_f32 v[226:227], v[226:227], v[226:227] op_sel:[0,1] op_sel_hi:[1,0]
	v_pk_add_f32 v[232:233], v[232:233], v[232:233] op_sel:[0,1] op_sel_hi:[1,0]
	v_pk_fma_f32 v[234:235], v[20:21], v[196:197], v[152:153] op_sel_hi:[1,0,1]
	v_mov_b32_e32 v227, v170
	v_mov_b32_e32 v233, v250
	v_mul_f32_e32 v170, v237, v237
	v_mul_f32_e32 v251, v246, v246
	v_pk_add_f32 v[226:227], v[226:227], v[232:233]
	v_pk_fma_f32 v[232:233], v[236:237], v[236:237], v[170:171] op_sel_hi:[1,1,0]
	v_mul_f32_e32 v170, v235, v235
	v_mul_f32_e32 v252, v247, v247
	v_mov_b32_e32 v233, v251
	v_pk_fma_f32 v[250:251], v[234:235], v[234:235], v[170:171] op_sel_hi:[1,1,0]
	v_pk_fma_f32 v[160:161], v[24:25], v[194:195], v[160:161] op_sel_hi:[1,0,1]
	v_mov_b32_e32 v251, v252
	v_pk_add_f32 v[232:233], v[232:233], v[250:251]
	v_pk_fma_f32 v[158:159], v[22:23], v[194:195], v[158:159] op_sel_hi:[1,0,1]
	v_pk_add_f32 v[226:227], v[226:227], v[232:233]
	v_pk_fma_f32 v[156:157], v[12:13], v[194:195], v[156:157] op_sel_hi:[1,0,1]
	v_add_f32_e32 v170, v226, v227
	ds_bpermute_b32 v226, v244, v170
	v_pk_fma_f32 v[154:155], v[10:11], v[194:195], v[154:155] op_sel_hi:[1,0,1]
	v_pk_fma_f32 v[146:147], v[2:3], v[194:195], v[146:147] op_sel_hi:[1,0,1]
	v_pk_fma_f32 v[150:151], v[6:7], v[194:195], v[150:151] op_sel_hi:[1,0,1]
	v_pk_fma_f32 v[152:153], v[8:9], v[194:195], v[152:153] op_sel_hi:[1,0,1]
	s_waitcnt lgkmcnt(0)
	v_add_f32_e32 v170, v170, v226
	ds_bpermute_b32 v226, v243, v170
	v_pk_fma_f32 v[148:149], v[4:5], v[194:195], v[148:149] op_sel_hi:[1,0,1]
	s_waitcnt lgkmcnt(0)
; __device__ __forceinline__ unsigned cvt_pk_bf16(float lo, float hi) { f32x2_t v = {lo, hi}; bf16x2_t b = __builtin_convertvector(v, bf16x2_t); return __builtin_bit_cast(unsigned, b); }
;     __device__ __forceinline__ void operator()(const f32x4 (&acc)[2][2][4][2], const Unit& u, int wr, int wc, int fr, int fq) const {
;     ...
;                 for (int m = 0; m < 4; ++m) {
;                     f32x4 v[2][2]; float ss = 0.f;
; #pragma unroll
;                     for (int bj = 0; bj < 2; ++bj)
; #pragma unroll
;                         for (int n = 0; n < 2; ++n) { v[bj][n] = acc[ai][bj][m][n] * rs[ai][m] + s4[bj][n]; const f32x4 t = v[bj][n]; ss += (t[0] * t[0] + t[1] * t[1]) + (t[2] * t[2] + t[3] * t[3]); }
;                     ss += __shfl_xor(ss, 16); ss += __shfl_xor(ss, 32);
;                     const float rq = __builtin_amdgcn_rsqf(ss * (1.0f / 64.0f) + EPS) * sc;
;                     bf16_t* rowp = O + (size_t)(row0 + ai * HALF + m * 16) * D + col0;
; #pragma unroll
;                     for (int bj = 0; bj < 2; ++bj) { const f32x4 v0 = v[bj][0] * rq * w4[bj][0], v1 = v[bj][1] * rq * w4[bj][1];
;                         u32x4 w; w.x = cvt_pk_bf16(v0[0], v0[1]); w.y = cvt_pk_bf16(v0[2], v0[3]); w.z = cvt_pk_bf16(v1[0], v1[1]); w.w = cvt_pk_bf16(v1[2], v1[3]);
;                         *(u32x4*)(rowp + 32 * bj) = w; } }
	v_add_f32_e32 v170, v170, v226
	v_fmamk_f32 v170, v170, 0x3c800000, v239
	v_rsq_f32_e32 v170, v170
	v_lshlrev_b64 v[226:227], 11, v[180:181]
	v_lshl_add_u64 v[226:227], v[220:221], 0, v[226:227]
	v_mul_f32_e32 v170, v245, v170
	v_pk_mul_f32 v[224:225], v[224:225], v[170:171] op_sel_hi:[1,0]
	v_pk_mul_f32 v[222:223], v[222:223], v[170:171] op_sel_hi:[1,0]
	v_pk_mul_f32 v[228:229], v[228:229], v[170:171] op_sel_hi:[1,0]
	v_pk_mul_f32 v[232:233], v[144:145], v[222:223]
	v_pk_mul_f32 v[222:223], v[142:143], v[224:225]
	v_pk_mul_f32 v[224:225], v[230:231], v[170:171] op_sel_hi:[1,0]
	v_pk_mul_f32 v[228:229], v[140:141], v[228:229]
	v_pk_mul_f32 v[224:225], v[138:139], v[224:225]
	v_cvt_pk_bf16_f32 v222, v222, v223
	v_cvt_pk_bf16_f32 v223, v232, v233
	v_cvt_pk_bf16_f32 v224, v224, v225
	v_cvt_pk_bf16_f32 v225, v228, v229
	global_store_dwordx4 v[226:227], v[222:225], off
	v_pk_mul_f32 v[228:229], v[248:249], v[170:171] op_sel_hi:[1,0]
	v_pk_mul_f32 v[230:231], v[246:247], v[170:171] op_sel_hi:[1,0]
	v_pk_mul_f32 v[222:223], v[236:237], v[170:171] op_sel_hi:[1,0]
	v_pk_mul_f32 v[224:225], v[234:235], v[170:171] op_sel_hi:[1,0]
	v_pk_mul_f32 v[222:223], v[134:135], v[222:223]
	v_pk_mul_f32 v[224:225], v[136:137], v[224:225]
	v_pk_mul_f32 v[230:231], v[132:133], v[230:231]
	v_pk_mul_f32 v[228:229], v[130:131], v[228:229]
	v_cvt_pk_bf16_f32 v222, v222, v223
	v_cvt_pk_bf16_f32 v223, v224, v225
	v_cvt_pk_bf16_f32 v224, v228, v229
	v_cvt_pk_bf16_f32 v225, v230, v231
	global_store_dwordx4 v[226:227], v[222:225], off offset:64
	v_mul_f32_e32 v170, v146, v146
	s_nop 0
	v_pk_mul_f32 v[222:223], v[160:161], v[160:161]
	v_pk_mul_f32 v[224:225], v[158:159], v[158:159]
	s_nop 0
	v_pk_mov_b32 v[226:227], v[224:225], v[222:223] op_sel:[1,0]
	v_mov_b32_e32 v225, v223
	v_pk_add_f32 v[222:223], v[226:227], v[224:225]
	v_pk_mul_f32 v[224:225], v[156:157], v[156:157]
	v_pk_mul_f32 v[226:227], v[154:155], v[154:155]
	v_pk_add_f32 v[222:223], v[222:223], v[222:223] op_sel:[0,1] op_sel_hi:[1,0]
	v_pk_mov_b32 v[228:229], v[226:227], v[224:225] op_sel:[1,0]
	v_mov_b32_e32 v227, v225
	v_pk_add_f32 v[224:225], v[228:229], v[226:227]
	v_mul_f32_e32 v226, v147, v147
	v_pk_add_f32 v[224:225], v[224:225], v[224:225] op_sel:[0,1] op_sel_hi:[1,0]
	v_mov_b32_e32 v223, v170
	v_mov_b32_e32 v225, v226
	v_mul_f32_e32 v170, v151, v151
	v_mul_f32_e32 v227, v148, v148
	v_pk_add_f32 v[222:223], v[222:223], v[224:225]
	v_pk_fma_f32 v[224:225], v[150:151], v[150:151], v[170:171] op_sel_hi:[1,1,0]
	v_mul_f32_e32 v170, v153, v153
	v_mul_f32_e32 v228, v149, v149
	v_mov_b32_e32 v225, v227
	v_pk_fma_f32 v[226:227], v[152:153], v[152:153], v[170:171] op_sel_hi:[1,1,0]
	s_nop 0
	v_mov_b32_e32 v227, v228
	v_pk_add_f32 v[224:225], v[224:225], v[226:227]
	s_nop 0
	v_pk_add_f32 v[222:223], v[222:223], v[224:225]
	s_nop 0
	v_add_f32_e32 v170, v222, v223
	v_mov_b32_e32 v254, v170
	v_mov_b32_e32 v222, v170
	s_nop 1
	v_permlane16_swap_b32_e32 v254, v222
	s_nop 0
	v_add_f32_e32 v170, v254, v222
	v_mov_b32_e32 v254, v170
	v_mov_b32_e32 v222, v170
	s_nop 1
	v_permlane32_swap_b32_e32 v254, v222
	s_nop 0
	v_add_f32_e32 v170, v254, v222
	v_fmamk_f32 v170, v170, 0x3c800000, v239
	v_rsq_f32_e32 v170, v170
	v_lshlrev_b64 v[222:223], 11, v[178:179]
	v_lshl_add_u64 v[220:221], v[220:221], 0, v[222:223]
	v_mul_f32_e32 v170, v245, v170
	v_pk_mul_f32 v[158:159], v[158:159], v[170:171] op_sel_hi:[1,0]
	v_pk_mul_f32 v[160:161], v[160:161], v[170:171] op_sel_hi:[1,0]
	v_pk_mul_f32 v[154:155], v[154:155], v[170:171] op_sel_hi:[1,0]
	v_pk_mul_f32 v[156:157], v[156:157], v[170:171] op_sel_hi:[1,0]
	v_pk_mul_f32 v[144:145], v[144:145], v[160:161]
	v_pk_mul_f32 v[142:143], v[142:143], v[158:159]
	v_pk_mul_f32 v[156:157], v[140:141], v[156:157]
	v_pk_mul_f32 v[140:141], v[138:139], v[154:155]
	v_cvt_pk_bf16_f32 v138, v142, v143
	v_cvt_pk_bf16_f32 v139, v144, v145
	v_cvt_pk_bf16_f32 v140, v140, v141
	v_cvt_pk_bf16_f32 v141, v156, v157
	global_store_dwordx4 v[220:221], v[138:141], off
	s_nop 1
	v_pk_mul_f32 v[138:139], v[150:151], v[170:171] op_sel_hi:[1,0]
	v_pk_mul_f32 v[140:141], v[152:153], v[170:171] op_sel_hi:[1,0]
	v_pk_mul_f32 v[134:135], v[134:135], v[138:139]
	v_pk_mul_f32 v[136:137], v[136:137], v[140:141]
	v_pk_mul_f32 v[138:139], v[146:147], v[170:171] op_sel_hi:[1,0]
	v_pk_mul_f32 v[140:141], v[148:149], v[170:171] op_sel_hi:[1,0]
	s_nop 0
	v_pk_mul_f32 v[140:141], v[132:133], v[140:141]
	v_pk_mul_f32 v[132:133], v[130:131], v[138:139]
	v_cvt_pk_bf16_f32 v130, v134, v135
	v_cvt_pk_bf16_f32 v131, v136, v137
	v_cvt_pk_bf16_f32 v132, v132, v133
	v_cvt_pk_bf16_f32 v133, v140, v141
	global_store_dwordx4 v[220:221], v[130:133], off offset:64
